# grid barrier: L1 invalidate issued by wave 1 (ordered before the arrival atomic by an extra s_barrier) so the arrival atomic's return no longer waits behind it
# speedup vs baseline: 1.2827x; 1.0239x over previous
.LBB0_191:
	s_andn2_b64 vcc, exec, s[2:3]
	s_cbranch_vccnz .LBB0_247
	v_readlane_b32 s10, v164, 0
	v_readlane_b32 s11, v162, 14
	v_readlane_b32 s16, v163, 15
	v_readlane_b32 s17, v163, 16
	v_readlane_b32 s18, v163, 5
	v_readlane_b32 s19, v163, 6
	s_mul_i32 s4, s34, 0x1600000
	s_add_u32 s18, s18, s4
	s_addc_u32 s19, s19, 0
	s_movk_i32 s42, 0x800
	v_and_b32_e32 v220, 63, v128
	v_lshrrev_b32_e32 v221, 6, v128
	v_and_b32_e32 v222, 15, v220
	v_lshrrev_b32_e32 v223, 4, v220
	v_readfirstlane_b32 s40, v221
	v_bfe_u32 v224, v222, 1, 3
	s_lshl_b32 s13, s40, 10
	s_and_b32 s36, s40, 1
	s_lshr_b32 s35, s40, 1
	v_xor_b32_e32 v225, v223, v224
	v_lshlrev_b32_e32 v225, 4, v225
	s_mul_i32 s4, s35, 0x50
	v_add_u32_e32 v226, s4, v222
	v_lshl_add_u32 v116, v226, 7, v225
	v_xor_b32_e32 v118, 64, v116
	s_lshl_b32 s4, s36, 6
	v_add_u32_e32 v227, s4, v222
	v_lshl_add_u32 v119, v227, 7, v225
	v_xor_b32_e32 v160, 64, v119
	v_and_b32_e32 v228, 7, v220
	v_lshrrev_b32_e32 v229, 3, v220
	v_xor_b32_e32 v230, v228, v223
	s_lshl_b32 s4, s36, 2
	v_xor_b32_e32 v230, s4, v230
	v_lshlrev_b32_e32 v230, 4, v230
	s_lshl_b32 s4, s40, 3
	v_add_u32_e32 v231, s4, v229
	v_mad_u32_u24 v161, v231, s42, v230
	v_bfe_u32 v232, v231, 2, 2
	v_and_b32_e32 v233, 3, v231
	v_lshrrev_b32_e32 v234, 4, v231
	v_lshl_add_u32 v232, v232, 3, v233
	s_movk_i32 s4, 0xb00
	v_mad_u32_u24 v232, v234, s4, v232
	v_mad_u32_u24 v165, v232, s42, v230
	v_mul_u32_u24_e32 v167, 0x1600, v226
	v_lshl_add_u32 v167, v223, 4, v167
	s_lshl_b32 s4, s36, 6
	v_add_u32_e32 v167, s4, v167
	s_movk_i32 s50, 0x580
	s_sub_u32 s51, s50, 1
	s_cmp_ge_u32 s10, s50
	s_cbranch_scc1 .Lggu0_done
	s_getreg_b32 s4, hwreg(HW_REG_HW_ID, 0, 4)
	s_and_b32 s4, s4, 1
	s_cmp_eq_u32 s4, 0
	s_cbranch_scc1 .Lggu0_noprio
	s_setprio 1

.Lggu0_tile:
	v_mov_b32_e32 v0, 0
	v_mov_b32_e32 v1, 0
	v_mov_b32_e32 v2, 0
	v_mov_b32_e32 v3, 0
	v_mov_b32_e32 v4, 0
	v_mov_b32_e32 v5, 0
	v_mov_b32_e32 v6, 0
	v_mov_b32_e32 v7, 0
	v_mov_b32_e32 v8, 0
	v_mov_b32_e32 v9, 0
	v_mov_b32_e32 v10, 0
	v_mov_b32_e32 v11, 0
	v_mov_b32_e32 v12, 0
	v_mov_b32_e32 v13, 0
	v_mov_b32_e32 v14, 0
	v_mov_b32_e32 v15, 0
	v_mov_b32_e32 v16, 0
	v_mov_b32_e32 v17, 0
	v_mov_b32_e32 v18, 0
	v_mov_b32_e32 v19, 0
	v_mov_b32_e32 v20, 0
	v_mov_b32_e32 v21, 0
	v_mov_b32_e32 v22, 0
	v_mov_b32_e32 v23, 0
	v_mov_b32_e32 v24, 0
	v_mov_b32_e32 v25, 0
	v_mov_b32_e32 v26, 0
	v_mov_b32_e32 v27, 0
	v_mov_b32_e32 v28, 0
	v_mov_b32_e32 v29, 0
	v_mov_b32_e32 v30, 0
	v_mov_b32_e32 v31, 0
	v_mov_b32_e32 v32, 0
	v_mov_b32_e32 v33, 0
	v_mov_b32_e32 v34, 0
	v_mov_b32_e32 v35, 0
	v_mov_b32_e32 v36, 0
	v_mov_b32_e32 v37, 0
	v_mov_b32_e32 v38, 0
	v_mov_b32_e32 v39, 0
	v_mov_b32_e32 v40, 0
	v_mov_b32_e32 v41, 0
	v_mov_b32_e32 v42, 0
	v_mov_b32_e32 v43, 0
	v_mov_b32_e32 v44, 0
	v_mov_b32_e32 v45, 0
	v_mov_b32_e32 v46, 0
	v_mov_b32_e32 v47, 0
	v_mov_b32_e32 v48, 0
	v_mov_b32_e32 v49, 0
	v_mov_b32_e32 v50, 0
	v_mov_b32_e32 v51, 0
	v_mov_b32_e32 v52, 0
	v_mov_b32_e32 v53, 0
	v_mov_b32_e32 v54, 0
	v_mov_b32_e32 v55, 0
	v_mov_b32_e32 v56, 0
	v_mov_b32_e32 v57, 0
	v_mov_b32_e32 v58, 0
	v_mov_b32_e32 v59, 0
	v_mov_b32_e32 v60, 0
	v_mov_b32_e32 v61, 0
	v_mov_b32_e32 v62, 0
	v_mov_b32_e32 v63, 0
	v_mov_b32_e32 v64, 0
	v_mov_b32_e32 v65, 0
	v_mov_b32_e32 v66, 0
	v_mov_b32_e32 v67, 0
	v_mov_b32_e32 v68, 0
	v_mov_b32_e32 v69, 0
	v_mov_b32_e32 v70, 0
	v_mov_b32_e32 v71, 0
	v_mov_b32_e32 v72, 0
	v_mov_b32_e32 v73, 0
	v_mov_b32_e32 v74, 0
	v_mov_b32_e32 v75, 0
	v_mov_b32_e32 v76, 0
	v_mov_b32_e32 v77, 0
	v_mov_b32_e32 v78, 0
	v_mov_b32_e32 v79, 0
	v_mov_b32_e32 v80, 0
	v_mov_b32_e32 v81, 0
	v_mov_b32_e32 v82, 0
	v_mov_b32_e32 v83, 0
	v_mov_b32_e32 v84, 0
	v_mov_b32_e32 v85, 0
	v_mov_b32_e32 v86, 0
	v_mov_b32_e32 v87, 0
	v_mov_b32_e32 v88, 0
	v_mov_b32_e32 v89, 0
	v_mov_b32_e32 v90, 0
	v_mov_b32_e32 v91, 0
	v_mov_b32_e32 v92, 0
	v_mov_b32_e32 v93, 0
	v_mov_b32_e32 v94, 0
	v_mov_b32_e32 v95, 0
	v_mov_b32_e32 v96, 0
	v_mov_b32_e32 v97, 0
	v_mov_b32_e32 v98, 0
	v_mov_b32_e32 v99, 0
	v_mov_b32_e32 v100, 0
	v_mov_b32_e32 v101, 0
	v_mov_b32_e32 v102, 0
	v_mov_b32_e32 v103, 0
	v_mov_b32_e32 v104, 0
	v_mov_b32_e32 v105, 0
	v_mov_b32_e32 v106, 0
	v_mov_b32_e32 v107, 0
	v_mov_b32_e32 v108, 0
	v_mov_b32_e32 v109, 0
	v_mov_b32_e32 v110, 0
	v_mov_b32_e32 v111, 0
	v_mov_b32_e32 v112, 0
	v_mov_b32_e32 v113, 0
	v_mov_b32_e32 v114, 0
	v_mov_b32_e32 v115, 0
	v_mov_b32_e32 v120, 0
	v_mov_b32_e32 v121, 0
	v_mov_b32_e32 v122, 0
	v_mov_b32_e32 v123, 0
	v_mov_b32_e32 v124, 0
	v_mov_b32_e32 v125, 0
	v_mov_b32_e32 v126, 0
	v_mov_b32_e32 v127, 0
	v_mov_b32_e32 v140, 0
	v_mov_b32_e32 v141, 0
	v_mov_b32_e32 v142, 0
	v_mov_b32_e32 v143, 0
	v_mov_b32_e32 v144, 0
	v_mov_b32_e32 v145, 0
	v_mov_b32_e32 v146, 0
	v_mov_b32_e32 v147, 0
	v_mov_b32_e32 v148, 0
	v_mov_b32_e32 v149, 0
	v_mov_b32_e32 v150, 0
	v_mov_b32_e32 v151, 0
	v_mov_b32_e32 v152, 0
	v_mov_b32_e32 v153, 0
	v_mov_b32_e32 v154, 0
	v_mov_b32_e32 v155, 0
	v_mov_b32_e32 v156, 0
	v_mov_b32_e32 v157, 0
	v_mov_b32_e32 v158, 0
	v_mov_b32_e32 v159, 0
	v_mov_b32_e32 v168, 0
	v_mov_b32_e32 v169, 0
	v_mov_b32_e32 v170, 0
	v_mov_b32_e32 v171, 0
	v_mov_b32_e32 v172, 0
	v_mov_b32_e32 v173, 0
	v_mov_b32_e32 v174, 0
	v_mov_b32_e32 v175, 0
	v_mov_b32_e32 v176, 0
	v_mov_b32_e32 v177, 0
	v_mov_b32_e32 v178, 0
	v_mov_b32_e32 v179, 0
	v_mov_b32_e32 v180, 0
	v_mov_b32_e32 v181, 0
	v_mov_b32_e32 v182, 0
	v_mov_b32_e32 v183, 0
	s_add_u32 s14, s10, s11
	s_min_u32 s14, s14, s51
	s_and_b32 s4, s14, 7
	s_lshl_b32 s4, s4, 3
	s_bfe_u32 s32, s14, 0x30003
	s_or_b32 s4, s4, s32
	s_mul_i32 s4, s4, 0x50000
	s_add_u32 s20, s16, s4
	s_addc_u32 s21, s17, 0
	s_lshr_b32 s4, s14, 6
	s_mul_i32 s4, s4, 0x40000
	s_add_u32 s22, s18, s4
	s_addc_u32 s23, s19, 0
	s_movk_i32 s12, 0x8

.Lggu0_wd:
	s_barrier
	ds_read_b128 v[184:187], v116 offset:0
	ds_read_b128 v[204:207], v119 offset:20480
	ds_read_b128 v[208:211], v119 offset:22528
	ds_read_b128 v[212:215], v119 offset:24576
	ds_read_b128 v[216:219], v119 offset:26624
	ds_read_b128 v[188:191], v116 offset:2048
	ds_read_b128 v[192:195], v116 offset:4096
	ds_read_b128 v[196:199], v116 offset:6144
	ds_read_b128 v[200:203], v116 offset:8192
	s_waitcnt lgkmcnt(7)
	v_mfma_f32_16x16x32_bf16 v[0:3], v[204:207], v[184:187], v[0:3]
	s_add_u32 m0, s13, 0x9000
	s_nop 0
	global_load_lds_dwordx4 v165, s[24:25]
	s_waitcnt lgkmcnt(6)
	v_mfma_f32_16x16x32_bf16 v[4:7], v[208:211], v[184:187], v[4:7]
	s_add_u32 m0, s13, 0xa000
	v_add_u32_e32 v166, 0x2000, v165
	global_load_lds_dwordx4 v166, s[24:25]
	s_waitcnt lgkmcnt(5)
	v_mfma_f32_16x16x32_bf16 v[8:11], v[212:215], v[184:187], v[8:11]
	s_add_u32 m0, s13, 0xb000
	v_add_u32_e32 v166, 0x10000, v165
	global_load_lds_dwordx4 v166, s[24:25]
	s_waitcnt lgkmcnt(4)
	v_mfma_f32_16x16x32_bf16 v[12:15], v[216:219], v[184:187], v[12:15]
	s_add_u32 m0, s13, 0xc000
	v_add_u32_e32 v166, 0x12000, v165
	global_load_lds_dwordx4 v166, s[24:25]
	ds_read_b128 v[220:223], v118 offset:0
	ds_read_b128 v[240:243], v160 offset:20480
	ds_read_b128 v[244:247], v160 offset:22528
	ds_read_b128 v[248:251], v160 offset:24576
	ds_read_b128 v[252:255], v160 offset:26624
	s_waitcnt lgkmcnt(8)
	v_mfma_f32_16x16x32_bf16 v[16:19], v[204:207], v[188:191], v[16:19]
	v_mfma_f32_16x16x32_bf16 v[20:23], v[208:211], v[188:191], v[20:23]
	v_mfma_f32_16x16x32_bf16 v[24:27], v[212:215], v[188:191], v[24:27]
	v_mfma_f32_16x16x32_bf16 v[28:31], v[216:219], v[188:191], v[28:31]
	ds_read_b128 v[224:227], v118 offset:2048
	ds_read_b128 v[228:231], v118 offset:4096
	ds_read_b128 v[232:235], v118 offset:6144
	ds_read_b128 v[236:239], v118 offset:8192
	s_waitcnt lgkmcnt(11)
	v_mfma_f32_16x16x32_bf16 v[32:35], v[204:207], v[192:195], v[32:35]
	v_mfma_f32_16x16x32_bf16 v[36:39], v[208:211], v[192:195], v[36:39]
	v_mfma_f32_16x16x32_bf16 v[40:43], v[212:215], v[192:195], v[40:43]
	v_mfma_f32_16x16x32_bf16 v[44:47], v[216:219], v[192:195], v[44:47]
	s_waitcnt lgkmcnt(10)
	v_mfma_f32_16x16x32_bf16 v[48:51], v[204:207], v[196:199], v[48:51]
	v_mfma_f32_16x16x32_bf16 v[52:55], v[208:211], v[196:199], v[52:55]
	v_mfma_f32_16x16x32_bf16 v[56:59], v[212:215], v[196:199], v[56:59]
	v_mfma_f32_16x16x32_bf16 v[60:63], v[216:219], v[196:199], v[60:63]
	s_waitcnt lgkmcnt(9)
	v_mfma_f32_16x16x32_bf16 v[64:67], v[204:207], v[200:203], v[64:67]
	v_mfma_f32_16x16x32_bf16 v[68:71], v[208:211], v[200:203], v[68:71]
	v_mfma_f32_16x16x32_bf16 v[72:75], v[212:215], v[200:203], v[72:75]
	v_mfma_f32_16x16x32_bf16 v[76:79], v[216:219], v[200:203], v[76:79]
	s_waitcnt lgkmcnt(7)
	v_mfma_f32_16x16x32_bf16 v[0:3], v[240:243], v[220:223], v[0:3]
	s_waitcnt lgkmcnt(6)
	v_mfma_f32_16x16x32_bf16 v[4:7], v[244:247], v[220:223], v[4:7]
	s_waitcnt lgkmcnt(5)
	v_mfma_f32_16x16x32_bf16 v[8:11], v[248:251], v[220:223], v[8:11]
	s_waitcnt lgkmcnt(4)
	v_mfma_f32_16x16x32_bf16 v[12:15], v[252:255], v[220:223], v[12:15]
	s_waitcnt lgkmcnt(3)
	v_mfma_f32_16x16x32_bf16 v[16:19], v[240:243], v[224:227], v[16:19]
	v_mfma_f32_16x16x32_bf16 v[20:23], v[244:247], v[224:227], v[20:23]
	v_mfma_f32_16x16x32_bf16 v[24:27], v[248:251], v[224:227], v[24:27]
	v_mfma_f32_16x16x32_bf16 v[28:31], v[252:255], v[224:227], v[28:31]
	s_waitcnt lgkmcnt(2)
	v_mfma_f32_16x16x32_bf16 v[32:35], v[240:243], v[228:231], v[32:35]
	v_mfma_f32_16x16x32_bf16 v[36:39], v[244:247], v[228:231], v[36:39]
	v_mfma_f32_16x16x32_bf16 v[40:43], v[248:251], v[228:231], v[40:43]
	v_mfma_f32_16x16x32_bf16 v[44:47], v[252:255], v[228:231], v[44:47]
	s_waitcnt lgkmcnt(1)
	v_mfma_f32_16x16x32_bf16 v[48:51], v[240:243], v[232:235], v[48:51]
	v_mfma_f32_16x16x32_bf16 v[52:55], v[244:247], v[232:235], v[52:55]
	v_mfma_f32_16x16x32_bf16 v[56:59], v[248:251], v[232:235], v[56:59]
	v_mfma_f32_16x16x32_bf16 v[60:63], v[252:255], v[232:235], v[60:63]
	s_add_u32 s24, s24, 0x80
	s_addc_u32 s25, s25, 0
	s_waitcnt lgkmcnt(0)
	v_mfma_f32_16x16x32_bf16 v[64:67], v[240:243], v[236:239], v[64:67]
	v_mfma_f32_16x16x32_bf16 v[68:71], v[244:247], v[236:239], v[68:71]
	v_mfma_f32_16x16x32_bf16 v[72:75], v[248:251], v[236:239], v[72:75]
	v_mfma_f32_16x16x32_bf16 v[76:79], v[252:255], v[236:239], v[76:79]
	s_waitcnt vmcnt(0)
	s_barrier
	ds_read_b128 v[184:187], v116 offset:0
	ds_read_b128 v[204:207], v119 offset:36864
	ds_read_b128 v[208:211], v119 offset:38912
	ds_read_b128 v[212:215], v119 offset:40960
	ds_read_b128 v[216:219], v119 offset:43008
	ds_read_b128 v[188:191], v116 offset:2048
	ds_read_b128 v[192:195], v116 offset:4096
	ds_read_b128 v[196:199], v116 offset:6144
	ds_read_b128 v[200:203], v116 offset:8192
	s_waitcnt lgkmcnt(7)
	v_mfma_f32_16x16x32_bf16 v[80:83], v[204:207], v[184:187], v[80:83]
	s_add_u32 m0, s13, 0xd100
	s_nop 0
	global_load_lds_dwordx4 v161, s[2:3]
	s_waitcnt lgkmcnt(6)
	v_mfma_f32_16x16x32_bf16 v[84:87], v[208:211], v[184:187], v[84:87]
	s_add_u32 m0, s13, 0xe100
	v_add_u32_e32 v166, 0x10000, v161
	global_load_lds_dwordx4 v166, s[2:3]
	s_waitcnt lgkmcnt(5)
	v_mfma_f32_16x16x32_bf16 v[88:91], v[212:215], v[184:187], v[88:91]
	s_add_u32 m0, s13, 0xf100
	v_add_u32_e32 v166, 0x20000, v161
	global_load_lds_dwordx4 v166, s[2:3]
	s_waitcnt lgkmcnt(4)
	v_mfma_f32_16x16x32_bf16 v[92:95], v[216:219], v[184:187], v[92:95]
	s_add_u32 m0, s13, 0x10100
	v_add_u32_e32 v166, 0x30000, v161
	global_load_lds_dwordx4 v166, s[2:3]
	ds_read_b128 v[220:223], v118 offset:0
	ds_read_b128 v[240:243], v160 offset:36864
	ds_read_b128 v[244:247], v160 offset:38912
	ds_read_b128 v[248:251], v160 offset:40960
	ds_read_b128 v[252:255], v160 offset:43008
	s_waitcnt lgkmcnt(8)
	v_mfma_f32_16x16x32_bf16 v[96:99], v[204:207], v[188:191], v[96:99]
	s_add_u32 m0, s13, 0x11100
	v_add_u32_e32 v166, 0x40000, v161
	global_load_lds_dwordx4 v166, s[2:3]
	v_mfma_f32_16x16x32_bf16 v[100:103], v[208:211], v[188:191], v[100:103]
	s_add_u32 m0, s13, 0x5000
	s_nop 0
	global_load_lds_dwordx4 v165, s[6:7]
	v_mfma_f32_16x16x32_bf16 v[104:107], v[212:215], v[188:191], v[104:107]
	s_add_u32 m0, s13, 0x6000
	v_add_u32_e32 v166, 0x2000, v165
	global_load_lds_dwordx4 v166, s[6:7]
	v_mfma_f32_16x16x32_bf16 v[108:111], v[216:219], v[188:191], v[108:111]
	s_add_u32 m0, s13, 0x7000
	v_add_u32_e32 v166, 0x10000, v165
	global_load_lds_dwordx4 v166, s[6:7]
	ds_read_b128 v[224:227], v118 offset:2048
	ds_read_b128 v[228:231], v118 offset:4096
	ds_read_b128 v[232:235], v118 offset:6144
	ds_read_b128 v[236:239], v118 offset:8192
	s_waitcnt lgkmcnt(11)
	v_mfma_f32_16x16x32_bf16 v[112:115], v[204:207], v[192:195], v[112:115]
	s_add_u32 m0, s13, 0x8000
	v_add_u32_e32 v166, 0x12000, v165
	global_load_lds_dwordx4 v166, s[6:7]
	v_mfma_f32_16x16x32_bf16 v[120:123], v[208:211], v[192:195], v[120:123]
	v_mfma_f32_16x16x32_bf16 v[124:127], v[212:215], v[192:195], v[124:127]
	v_mfma_f32_16x16x32_bf16 v[140:143], v[216:219], v[192:195], v[140:143]
	s_waitcnt lgkmcnt(10)
	v_mfma_f32_16x16x32_bf16 v[144:147], v[204:207], v[196:199], v[144:147]
	v_mfma_f32_16x16x32_bf16 v[148:151], v[208:211], v[196:199], v[148:151]
	v_mfma_f32_16x16x32_bf16 v[152:155], v[212:215], v[196:199], v[152:155]
	v_mfma_f32_16x16x32_bf16 v[156:159], v[216:219], v[196:199], v[156:159]
	s_waitcnt lgkmcnt(9)
	v_mfma_f32_16x16x32_bf16 v[168:171], v[204:207], v[200:203], v[168:171]
	v_mfma_f32_16x16x32_bf16 v[172:175], v[208:211], v[200:203], v[172:175]
	v_mfma_f32_16x16x32_bf16 v[176:179], v[212:215], v[200:203], v[176:179]
	v_mfma_f32_16x16x32_bf16 v[180:183], v[216:219], v[200:203], v[180:183]
	s_waitcnt lgkmcnt(7)
	v_mfma_f32_16x16x32_bf16 v[80:83], v[240:243], v[220:223], v[80:83]
	s_waitcnt lgkmcnt(6)
	v_mfma_f32_16x16x32_bf16 v[84:87], v[244:247], v[220:223], v[84:87]
	s_waitcnt lgkmcnt(5)
	v_mfma_f32_16x16x32_bf16 v[88:91], v[248:251], v[220:223], v[88:91]
	s_waitcnt lgkmcnt(4)
	v_mfma_f32_16x16x32_bf16 v[92:95], v[252:255], v[220:223], v[92:95]
	s_waitcnt lgkmcnt(3)
	v_mfma_f32_16x16x32_bf16 v[96:99], v[240:243], v[224:227], v[96:99]
	v_mfma_f32_16x16x32_bf16 v[100:103], v[244:247], v[224:227], v[100:103]
	v_mfma_f32_16x16x32_bf16 v[104:107], v[248:251], v[224:227], v[104:107]
	v_mfma_f32_16x16x32_bf16 v[108:111], v[252:255], v[224:227], v[108:111]
	s_waitcnt lgkmcnt(2)
	v_mfma_f32_16x16x32_bf16 v[112:115], v[240:243], v[228:231], v[112:115]
	v_mfma_f32_16x16x32_bf16 v[120:123], v[244:247], v[228:231], v[120:123]
	v_mfma_f32_16x16x32_bf16 v[124:127], v[248:251], v[228:231], v[124:127]
	v_mfma_f32_16x16x32_bf16 v[140:143], v[252:255], v[228:231], v[140:143]
	s_waitcnt lgkmcnt(1)
	v_mfma_f32_16x16x32_bf16 v[144:147], v[240:243], v[232:235], v[144:147]
	v_mfma_f32_16x16x32_bf16 v[148:151], v[244:247], v[232:235], v[148:151]
	v_mfma_f32_16x16x32_bf16 v[152:155], v[248:251], v[232:235], v[152:155]
	v_mfma_f32_16x16x32_bf16 v[156:159], v[252:255], v[232:235], v[156:159]
	s_add_u32 s2, s2, 0x80
	s_addc_u32 s3, s3, 0
	s_add_u32 s6, s6, 0x80
	s_addc_u32 s7, s7, 0
	s_waitcnt lgkmcnt(0)
	v_mfma_f32_16x16x32_bf16 v[168:171], v[240:243], v[236:239], v[168:171]
	v_mfma_f32_16x16x32_bf16 v[172:175], v[244:247], v[236:239], v[172:175]
	v_mfma_f32_16x16x32_bf16 v[176:179], v[248:251], v[236:239], v[176:179]
	v_mfma_f32_16x16x32_bf16 v[180:183], v[252:255], v[236:239], v[180:183]
	s_waitcnt vmcnt(0)
	s_barrier
	ds_read_b128 v[184:187], v116 offset:53504
	ds_read_b128 v[204:207], v119 offset:20480
	ds_read_b128 v[208:211], v119 offset:22528
	ds_read_b128 v[212:215], v119 offset:24576
	ds_read_b128 v[216:219], v119 offset:26624
	ds_read_b128 v[188:191], v116 offset:55552
	ds_read_b128 v[192:195], v116 offset:57600
	ds_read_b128 v[196:199], v116 offset:59648
	ds_read_b128 v[200:203], v116 offset:61696
	s_waitcnt lgkmcnt(7)
	v_mfma_f32_16x16x32_bf16 v[0:3], v[204:207], v[184:187], v[0:3]
	s_add_u32 m0, s13, 0x9000
	s_nop 0
	global_load_lds_dwordx4 v165, s[24:25]
	s_waitcnt lgkmcnt(6)
	v_mfma_f32_16x16x32_bf16 v[4:7], v[208:211], v[184:187], v[4:7]
	s_add_u32 m0, s13, 0xa000
	v_add_u32_e32 v166, 0x2000, v165
	global_load_lds_dwordx4 v166, s[24:25]
	s_waitcnt lgkmcnt(5)
	v_mfma_f32_16x16x32_bf16 v[8:11], v[212:215], v[184:187], v[8:11]
	s_add_u32 m0, s13, 0xb000
	v_add_u32_e32 v166, 0x10000, v165
	global_load_lds_dwordx4 v166, s[24:25]
	s_waitcnt lgkmcnt(4)
	v_mfma_f32_16x16x32_bf16 v[12:15], v[216:219], v[184:187], v[12:15]
	s_add_u32 m0, s13, 0xc000
	v_add_u32_e32 v166, 0x12000, v165
	global_load_lds_dwordx4 v166, s[24:25]
	ds_read_b128 v[220:223], v118 offset:53504
	ds_read_b128 v[240:243], v160 offset:20480
	ds_read_b128 v[244:247], v160 offset:22528
	ds_read_b128 v[248:251], v160 offset:24576
	ds_read_b128 v[252:255], v160 offset:26624
	s_waitcnt lgkmcnt(8)
	v_mfma_f32_16x16x32_bf16 v[16:19], v[204:207], v[188:191], v[16:19]
	v_mfma_f32_16x16x32_bf16 v[20:23], v[208:211], v[188:191], v[20:23]
	v_mfma_f32_16x16x32_bf16 v[24:27], v[212:215], v[188:191], v[24:27]
	v_mfma_f32_16x16x32_bf16 v[28:31], v[216:219], v[188:191], v[28:31]
	ds_read_b128 v[224:227], v118 offset:55552
	ds_read_b128 v[228:231], v118 offset:57600
	ds_read_b128 v[232:235], v118 offset:59648
	ds_read_b128 v[236:239], v118 offset:61696
	s_waitcnt lgkmcnt(11)
	v_mfma_f32_16x16x32_bf16 v[32:35], v[204:207], v[192:195], v[32:35]
	v_mfma_f32_16x16x32_bf16 v[36:39], v[208:211], v[192:195], v[36:39]
	v_mfma_f32_16x16x32_bf16 v[40:43], v[212:215], v[192:195], v[40:43]
	v_mfma_f32_16x16x32_bf16 v[44:47], v[216:219], v[192:195], v[44:47]
	s_waitcnt lgkmcnt(10)
	v_mfma_f32_16x16x32_bf16 v[48:51], v[204:207], v[196:199], v[48:51]
	v_mfma_f32_16x16x32_bf16 v[52:55], v[208:211], v[196:199], v[52:55]
	v_mfma_f32_16x16x32_bf16 v[56:59], v[212:215], v[196:199], v[56:59]
	v_mfma_f32_16x16x32_bf16 v[60:63], v[216:219], v[196:199], v[60:63]
	s_waitcnt lgkmcnt(9)
	v_mfma_f32_16x16x32_bf16 v[64:67], v[204:207], v[200:203], v[64:67]
	v_mfma_f32_16x16x32_bf16 v[68:71], v[208:211], v[200:203], v[68:71]
	v_mfma_f32_16x16x32_bf16 v[72:75], v[212:215], v[200:203], v[72:75]
	v_mfma_f32_16x16x32_bf16 v[76:79], v[216:219], v[200:203], v[76:79]
	s_waitcnt lgkmcnt(7)
	v_mfma_f32_16x16x32_bf16 v[0:3], v[240:243], v[220:223], v[0:3]
	s_waitcnt lgkmcnt(6)
	v_mfma_f32_16x16x32_bf16 v[4:7], v[244:247], v[220:223], v[4:7]
	s_waitcnt lgkmcnt(5)
	v_mfma_f32_16x16x32_bf16 v[8:11], v[248:251], v[220:223], v[8:11]
	s_waitcnt lgkmcnt(4)
	v_mfma_f32_16x16x32_bf16 v[12:15], v[252:255], v[220:223], v[12:15]
	s_waitcnt lgkmcnt(3)
	v_mfma_f32_16x16x32_bf16 v[16:19], v[240:243], v[224:227], v[16:19]
	v_mfma_f32_16x16x32_bf16 v[20:23], v[244:247], v[224:227], v[20:23]
	v_mfma_f32_16x16x32_bf16 v[24:27], v[248:251], v[224:227], v[24:27]
	v_mfma_f32_16x16x32_bf16 v[28:31], v[252:255], v[224:227], v[28:31]
	s_waitcnt lgkmcnt(2)
	v_mfma_f32_16x16x32_bf16 v[32:35], v[240:243], v[228:231], v[32:35]
	v_mfma_f32_16x16x32_bf16 v[36:39], v[244:247], v[228:231], v[36:39]
	v_mfma_f32_16x16x32_bf16 v[40:43], v[248:251], v[228:231], v[40:43]
	v_mfma_f32_16x16x32_bf16 v[44:47], v[252:255], v[228:231], v[44:47]
	s_waitcnt lgkmcnt(1)
	v_mfma_f32_16x16x32_bf16 v[48:51], v[240:243], v[232:235], v[48:51]
	v_mfma_f32_16x16x32_bf16 v[52:55], v[244:247], v[232:235], v[52:55]
	v_mfma_f32_16x16x32_bf16 v[56:59], v[248:251], v[232:235], v[56:59]
	v_mfma_f32_16x16x32_bf16 v[60:63], v[252:255], v[232:235], v[60:63]
	s_add_u32 s24, s24, 0x80
	s_addc_u32 s25, s25, 0
	s_waitcnt lgkmcnt(0)
	v_mfma_f32_16x16x32_bf16 v[64:67], v[240:243], v[236:239], v[64:67]
	v_mfma_f32_16x16x32_bf16 v[68:71], v[244:247], v[236:239], v[68:71]
	v_mfma_f32_16x16x32_bf16 v[72:75], v[248:251], v[236:239], v[72:75]
	v_mfma_f32_16x16x32_bf16 v[76:79], v[252:255], v[236:239], v[76:79]
	s_cmp_eq_u32 s12, 1
	s_cselect_b32 s2, s20, s2
	s_cselect_b32 s3, s21, s3
	s_cselect_b32 s6, s22, s6
	s_cselect_b32 s7, s23, s7
	s_add_u32 s4, s22, 0x20000
	s_addc_u32 s32, s23, 0
	s_cmp_eq_u32 s12, 1
	s_cselect_b32 s24, s4, s24
	s_cselect_b32 s25, s32, s25
	s_waitcnt vmcnt(0)
	s_barrier
	ds_read_b128 v[184:187], v116 offset:53504
	ds_read_b128 v[204:207], v119 offset:36864
	ds_read_b128 v[208:211], v119 offset:38912
	ds_read_b128 v[212:215], v119 offset:40960
	ds_read_b128 v[216:219], v119 offset:43008
	ds_read_b128 v[188:191], v116 offset:55552
	ds_read_b128 v[192:195], v116 offset:57600
	ds_read_b128 v[196:199], v116 offset:59648
	ds_read_b128 v[200:203], v116 offset:61696
	s_waitcnt lgkmcnt(7)
	v_mfma_f32_16x16x32_bf16 v[80:83], v[204:207], v[184:187], v[80:83]
	s_add_u32 m0, s13, 0x0
	s_nop 0
	global_load_lds_dwordx4 v161, s[2:3]
	s_waitcnt lgkmcnt(6)
	v_mfma_f32_16x16x32_bf16 v[84:87], v[208:211], v[184:187], v[84:87]
	s_add_u32 m0, s13, 0x1000
	v_add_u32_e32 v166, 0x10000, v161
	global_load_lds_dwordx4 v166, s[2:3]
	s_waitcnt lgkmcnt(5)
	v_mfma_f32_16x16x32_bf16 v[88:91], v[212:215], v[184:187], v[88:91]
	s_add_u32 m0, s13, 0x2000
	v_add_u32_e32 v166, 0x20000, v161
	global_load_lds_dwordx4 v166, s[2:3]
	s_waitcnt lgkmcnt(4)
	v_mfma_f32_16x16x32_bf16 v[92:95], v[216:219], v[184:187], v[92:95]
	s_add_u32 m0, s13, 0x3000
	v_add_u32_e32 v166, 0x30000, v161
	global_load_lds_dwordx4 v166, s[2:3]
	ds_read_b128 v[220:223], v118 offset:53504
	ds_read_b128 v[240:243], v160 offset:36864
	ds_read_b128 v[244:247], v160 offset:38912
	ds_read_b128 v[248:251], v160 offset:40960
	ds_read_b128 v[252:255], v160 offset:43008
	s_waitcnt lgkmcnt(8)
	v_mfma_f32_16x16x32_bf16 v[96:99], v[204:207], v[188:191], v[96:99]
	s_add_u32 m0, s13, 0x4000
	v_add_u32_e32 v166, 0x40000, v161
	global_load_lds_dwordx4 v166, s[2:3]
	v_mfma_f32_16x16x32_bf16 v[100:103], v[208:211], v[188:191], v[100:103]
	s_add_u32 m0, s13, 0x5000
	s_nop 0
	global_load_lds_dwordx4 v165, s[6:7]
	v_mfma_f32_16x16x32_bf16 v[104:107], v[212:215], v[188:191], v[104:107]
	s_add_u32 m0, s13, 0x6000
	v_add_u32_e32 v166, 0x2000, v165
	global_load_lds_dwordx4 v166, s[6:7]
	v_mfma_f32_16x16x32_bf16 v[108:111], v[216:219], v[188:191], v[108:111]
	s_add_u32 m0, s13, 0x7000
	v_add_u32_e32 v166, 0x10000, v165
	global_load_lds_dwordx4 v166, s[6:7]
	ds_read_b128 v[224:227], v118 offset:55552
	ds_read_b128 v[228:231], v118 offset:57600
	ds_read_b128 v[232:235], v118 offset:59648
	ds_read_b128 v[236:239], v118 offset:61696
	s_waitcnt lgkmcnt(11)
	v_mfma_f32_16x16x32_bf16 v[112:115], v[204:207], v[192:195], v[112:115]
	s_add_u32 m0, s13, 0x8000
	v_add_u32_e32 v166, 0x12000, v165
	global_load_lds_dwordx4 v166, s[6:7]
	v_mfma_f32_16x16x32_bf16 v[120:123], v[208:211], v[192:195], v[120:123]
	v_mfma_f32_16x16x32_bf16 v[124:127], v[212:215], v[192:195], v[124:127]
	v_mfma_f32_16x16x32_bf16 v[140:143], v[216:219], v[192:195], v[140:143]
	s_waitcnt lgkmcnt(10)
	v_mfma_f32_16x16x32_bf16 v[144:147], v[204:207], v[196:199], v[144:147]
	v_mfma_f32_16x16x32_bf16 v[148:151], v[208:211], v[196:199], v[148:151]
	v_mfma_f32_16x16x32_bf16 v[152:155], v[212:215], v[196:199], v[152:155]
	v_mfma_f32_16x16x32_bf16 v[156:159], v[216:219], v[196:199], v[156:159]
	s_waitcnt lgkmcnt(9)
	v_mfma_f32_16x16x32_bf16 v[168:171], v[204:207], v[200:203], v[168:171]
	v_mfma_f32_16x16x32_bf16 v[172:175], v[208:211], v[200:203], v[172:175]
	v_mfma_f32_16x16x32_bf16 v[176:179], v[212:215], v[200:203], v[176:179]
	v_mfma_f32_16x16x32_bf16 v[180:183], v[216:219], v[200:203], v[180:183]
	s_waitcnt lgkmcnt(7)
	v_mfma_f32_16x16x32_bf16 v[80:83], v[240:243], v[220:223], v[80:83]
	s_waitcnt lgkmcnt(6)
	v_mfma_f32_16x16x32_bf16 v[84:87], v[244:247], v[220:223], v[84:87]
	s_waitcnt lgkmcnt(5)
	v_mfma_f32_16x16x32_bf16 v[88:91], v[248:251], v[220:223], v[88:91]
	s_waitcnt lgkmcnt(4)
	v_mfma_f32_16x16x32_bf16 v[92:95], v[252:255], v[220:223], v[92:95]
	s_waitcnt lgkmcnt(3)
	v_mfma_f32_16x16x32_bf16 v[96:99], v[240:243], v[224:227], v[96:99]
	v_mfma_f32_16x16x32_bf16 v[100:103], v[244:247], v[224:227], v[100:103]
	v_mfma_f32_16x16x32_bf16 v[104:107], v[248:251], v[224:227], v[104:107]
	v_mfma_f32_16x16x32_bf16 v[108:111], v[252:255], v[224:227], v[108:111]
	s_waitcnt lgkmcnt(2)
	v_mfma_f32_16x16x32_bf16 v[112:115], v[240:243], v[228:231], v[112:115]
	v_mfma_f32_16x16x32_bf16 v[120:123], v[244:247], v[228:231], v[120:123]
	v_mfma_f32_16x16x32_bf16 v[124:127], v[248:251], v[228:231], v[124:127]
	v_mfma_f32_16x16x32_bf16 v[140:143], v[252:255], v[228:231], v[140:143]
	s_waitcnt lgkmcnt(1)
	v_mfma_f32_16x16x32_bf16 v[144:147], v[240:243], v[232:235], v[144:147]
	v_mfma_f32_16x16x32_bf16 v[148:151], v[244:247], v[232:235], v[148:151]
	v_mfma_f32_16x16x32_bf16 v[152:155], v[248:251], v[232:235], v[152:155]
	v_mfma_f32_16x16x32_bf16 v[156:159], v[252:255], v[232:235], v[156:159]
	s_add_u32 s2, s2, 0x80
	s_addc_u32 s3, s3, 0
	s_add_u32 s6, s6, 0x80
	s_addc_u32 s7, s7, 0
	s_waitcnt lgkmcnt(0)
	v_mfma_f32_16x16x32_bf16 v[168:171], v[240:243], v[236:239], v[168:171]
	v_mfma_f32_16x16x32_bf16 v[172:175], v[244:247], v[236:239], v[172:175]
	v_mfma_f32_16x16x32_bf16 v[176:179], v[248:251], v[236:239], v[176:179]
	v_mfma_f32_16x16x32_bf16 v[180:183], v[252:255], v[236:239], v[180:183]
	s_sub_u32 s12, s12, 1
	s_cmp_lg_u32 s12, 0
	s_cbranch_scc1 .Lggu0_pair
	s_and_b32 s4, s10, 7
	s_lshl_b32 s4, s4, 3
	s_bfe_u32 s14, s10, 0x30003
	s_or_b32 s14, s14, s4
	s_lshr_b32 s15, s10, 6
	s_mul_i32 s4, s14, 0xdc000
	s_lshl_b32 s32, s15, 8
	s_add_u32 s4, s4, s32
	s_add_u32 s8, s76, s4
	s_addc_u32 s9, s77, 0
	s_mov_b32 s44, s8
	s_mov_b32 s46, s9
	s_nop 7
	v_mul_f32_e32 v184, 0xbfb8aa3b, v0
	v_mul_f32_e32 v185, 0xbfb8aa3b, v1
	v_mul_f32_e32 v186, 0xbfb8aa3b, v2
	v_mul_f32_e32 v187, 0xbfb8aa3b, v3
	v_exp_f32_e32 v184, v184
	v_exp_f32_e32 v185, v185
	v_exp_f32_e32 v186, v186
	v_exp_f32_e32 v187, v187
	s_nop 0
	v_add_f32_e32 v184, 1.0, v184
	v_add_f32_e32 v185, 1.0, v185
	v_add_f32_e32 v186, 1.0, v186
	v_add_f32_e32 v187, 1.0, v187
	v_rcp_f32_e32 v184, v184
	v_rcp_f32_e32 v185, v185
	v_rcp_f32_e32 v186, v186
	v_rcp_f32_e32 v187, v187
	s_nop 0
	v_mul_f32_e32 v184, v0, v184
	v_mul_f32_e32 v185, v1, v185
	v_mul_f32_e32 v186, v2, v186
	v_mul_f32_e32 v187, v3, v187
	v_mul_f32_e32 v184, v4, v184
	v_mul_f32_e32 v185, v5, v185
	v_mul_f32_e32 v186, v6, v186
	v_mul_f32_e32 v187, v7, v187
	v_mul_f32_e32 v192, 0xbfb8aa3b, v8
	v_mul_f32_e32 v193, 0xbfb8aa3b, v9
	v_mul_f32_e32 v194, 0xbfb8aa3b, v10
	v_mul_f32_e32 v195, 0xbfb8aa3b, v11
	v_exp_f32_e32 v192, v192
	v_exp_f32_e32 v193, v193
	v_exp_f32_e32 v194, v194
	v_exp_f32_e32 v195, v195
	s_nop 0
	v_add_f32_e32 v192, 1.0, v192
	v_add_f32_e32 v193, 1.0, v193
	v_add_f32_e32 v194, 1.0, v194
	v_add_f32_e32 v195, 1.0, v195
	v_rcp_f32_e32 v192, v192
	v_rcp_f32_e32 v193, v193
	v_rcp_f32_e32 v194, v194
	v_rcp_f32_e32 v195, v195
	s_nop 0
	v_mul_f32_e32 v192, v8, v192
	v_mul_f32_e32 v193, v9, v193
	v_mul_f32_e32 v194, v10, v194
	v_mul_f32_e32 v195, v11, v195
	v_mul_f32_e32 v192, v12, v192
	v_mul_f32_e32 v193, v13, v193
	v_mul_f32_e32 v194, v14, v194
	v_mul_f32_e32 v195, v15, v195
	v_cvt_pk_bf16_f32 v200, v184, v185
	v_cvt_pk_bf16_f32 v201, v186, v187
	v_cvt_pk_bf16_f32 v202, v192, v193
	v_cvt_pk_bf16_f32 v203, v194, v195
	global_store_dwordx4 v167, v[200:203], s[8:9]
	s_add_u32 s8, s8, 0x16000
	s_addc_u32 s9, s9, 0
	v_mul_f32_e32 v184, 0xbfb8aa3b, v16
	v_mul_f32_e32 v185, 0xbfb8aa3b, v17
	v_mul_f32_e32 v186, 0xbfb8aa3b, v18
	v_mul_f32_e32 v187, 0xbfb8aa3b, v19
	v_exp_f32_e32 v184, v184
	v_exp_f32_e32 v185, v185
	v_exp_f32_e32 v186, v186
	v_exp_f32_e32 v187, v187
	s_nop 0
	v_add_f32_e32 v184, 1.0, v184
	v_add_f32_e32 v185, 1.0, v185
	v_add_f32_e32 v186, 1.0, v186
	v_add_f32_e32 v187, 1.0, v187
	v_rcp_f32_e32 v184, v184
	v_rcp_f32_e32 v185, v185
	v_rcp_f32_e32 v186, v186
	v_rcp_f32_e32 v187, v187
	s_nop 0
	v_mul_f32_e32 v184, v16, v184
	v_mul_f32_e32 v185, v17, v185
	v_mul_f32_e32 v186, v18, v186
	v_mul_f32_e32 v187, v19, v187
	v_mul_f32_e32 v184, v20, v184
	v_mul_f32_e32 v185, v21, v185
	v_mul_f32_e32 v186, v22, v186
	v_mul_f32_e32 v187, v23, v187
	v_mul_f32_e32 v192, 0xbfb8aa3b, v24
	v_mul_f32_e32 v193, 0xbfb8aa3b, v25
	v_mul_f32_e32 v194, 0xbfb8aa3b, v26
	v_mul_f32_e32 v195, 0xbfb8aa3b, v27
	v_exp_f32_e32 v192, v192
	v_exp_f32_e32 v193, v193
	v_exp_f32_e32 v194, v194
	v_exp_f32_e32 v195, v195
	s_nop 0
	v_add_f32_e32 v192, 1.0, v192
	v_add_f32_e32 v193, 1.0, v193
	v_add_f32_e32 v194, 1.0, v194
	v_add_f32_e32 v195, 1.0, v195
	v_rcp_f32_e32 v192, v192
	v_rcp_f32_e32 v193, v193
	v_rcp_f32_e32 v194, v194
	v_rcp_f32_e32 v195, v195
	s_nop 0
	v_mul_f32_e32 v192, v24, v192
	v_mul_f32_e32 v193, v25, v193
	v_mul_f32_e32 v194, v26, v194
	v_mul_f32_e32 v195, v27, v195
	v_mul_f32_e32 v192, v28, v192
	v_mul_f32_e32 v193, v29, v193
	v_mul_f32_e32 v194, v30, v194
	v_mul_f32_e32 v195, v31, v195
	v_cvt_pk_bf16_f32 v204, v184, v185
	v_cvt_pk_bf16_f32 v205, v186, v187
	v_cvt_pk_bf16_f32 v206, v192, v193
	v_cvt_pk_bf16_f32 v207, v194, v195
	global_store_dwordx4 v167, v[204:207], s[8:9]
	s_add_u32 s8, s8, 0x16000
	s_addc_u32 s9, s9, 0
	v_mul_f32_e32 v184, 0xbfb8aa3b, v32
	v_mul_f32_e32 v185, 0xbfb8aa3b, v33
	v_mul_f32_e32 v186, 0xbfb8aa3b, v34
	v_mul_f32_e32 v187, 0xbfb8aa3b, v35
	v_exp_f32_e32 v184, v184
	v_exp_f32_e32 v185, v185
	v_exp_f32_e32 v186, v186
	v_exp_f32_e32 v187, v187
	s_nop 0
	v_add_f32_e32 v184, 1.0, v184
	v_add_f32_e32 v185, 1.0, v185
	v_add_f32_e32 v186, 1.0, v186
	v_add_f32_e32 v187, 1.0, v187
	v_rcp_f32_e32 v184, v184
	v_rcp_f32_e32 v185, v185
	v_rcp_f32_e32 v186, v186
	v_rcp_f32_e32 v187, v187
	s_nop 0
	v_mul_f32_e32 v184, v32, v184
	v_mul_f32_e32 v185, v33, v185
	v_mul_f32_e32 v186, v34, v186
	v_mul_f32_e32 v187, v35, v187
	v_mul_f32_e32 v184, v36, v184
	v_mul_f32_e32 v185, v37, v185
	v_mul_f32_e32 v186, v38, v186
	v_mul_f32_e32 v187, v39, v187
	v_mul_f32_e32 v192, 0xbfb8aa3b, v40
	v_mul_f32_e32 v193, 0xbfb8aa3b, v41
	v_mul_f32_e32 v194, 0xbfb8aa3b, v42
	v_mul_f32_e32 v195, 0xbfb8aa3b, v43
	v_exp_f32_e32 v192, v192
	v_exp_f32_e32 v193, v193
	v_exp_f32_e32 v194, v194
	v_exp_f32_e32 v195, v195
	s_nop 0
	v_add_f32_e32 v192, 1.0, v192
	v_add_f32_e32 v193, 1.0, v193
	v_add_f32_e32 v194, 1.0, v194
	v_add_f32_e32 v195, 1.0, v195
	v_rcp_f32_e32 v192, v192
	v_rcp_f32_e32 v193, v193
	v_rcp_f32_e32 v194, v194
	v_rcp_f32_e32 v195, v195
	s_nop 0
	v_mul_f32_e32 v192, v40, v192
	v_mul_f32_e32 v193, v41, v193
	v_mul_f32_e32 v194, v42, v194
	v_mul_f32_e32 v195, v43, v195
	v_mul_f32_e32 v192, v44, v192
	v_mul_f32_e32 v193, v45, v193
	v_mul_f32_e32 v194, v46, v194
	v_mul_f32_e32 v195, v47, v195
	v_cvt_pk_bf16_f32 v208, v184, v185
	v_cvt_pk_bf16_f32 v209, v186, v187
	v_cvt_pk_bf16_f32 v210, v192, v193
	v_cvt_pk_bf16_f32 v211, v194, v195
	global_store_dwordx4 v167, v[208:211], s[8:9]
	s_add_u32 s8, s8, 0x16000
	s_addc_u32 s9, s9, 0
	v_mul_f32_e32 v184, 0xbfb8aa3b, v48
	v_mul_f32_e32 v185, 0xbfb8aa3b, v49
	v_mul_f32_e32 v186, 0xbfb8aa3b, v50
	v_mul_f32_e32 v187, 0xbfb8aa3b, v51
	v_exp_f32_e32 v184, v184
	v_exp_f32_e32 v185, v185
	v_exp_f32_e32 v186, v186
	v_exp_f32_e32 v187, v187
	s_nop 0
	v_add_f32_e32 v184, 1.0, v184
	v_add_f32_e32 v185, 1.0, v185
	v_add_f32_e32 v186, 1.0, v186
	v_add_f32_e32 v187, 1.0, v187
	v_rcp_f32_e32 v184, v184
	v_rcp_f32_e32 v185, v185
	v_rcp_f32_e32 v186, v186
	v_rcp_f32_e32 v187, v187
	s_nop 0
	v_mul_f32_e32 v184, v48, v184
	v_mul_f32_e32 v185, v49, v185
	v_mul_f32_e32 v186, v50, v186
	v_mul_f32_e32 v187, v51, v187
	v_mul_f32_e32 v184, v52, v184
	v_mul_f32_e32 v185, v53, v185
	v_mul_f32_e32 v186, v54, v186
	v_mul_f32_e32 v187, v55, v187
	v_mul_f32_e32 v192, 0xbfb8aa3b, v56
	v_mul_f32_e32 v193, 0xbfb8aa3b, v57
	v_mul_f32_e32 v194, 0xbfb8aa3b, v58
	v_mul_f32_e32 v195, 0xbfb8aa3b, v59
	v_exp_f32_e32 v192, v192
	v_exp_f32_e32 v193, v193
	v_exp_f32_e32 v194, v194
	v_exp_f32_e32 v195, v195
	s_nop 0
	v_add_f32_e32 v192, 1.0, v192
	v_add_f32_e32 v193, 1.0, v193
	v_add_f32_e32 v194, 1.0, v194
	v_add_f32_e32 v195, 1.0, v195
	v_rcp_f32_e32 v192, v192
	v_rcp_f32_e32 v193, v193
	v_rcp_f32_e32 v194, v194
	v_rcp_f32_e32 v195, v195
	s_nop 0
	v_mul_f32_e32 v192, v56, v192
	v_mul_f32_e32 v193, v57, v193
	v_mul_f32_e32 v194, v58, v194
	v_mul_f32_e32 v195, v59, v195
	v_mul_f32_e32 v192, v60, v192
	v_mul_f32_e32 v193, v61, v193
	v_mul_f32_e32 v194, v62, v194
	v_mul_f32_e32 v195, v63, v195
	v_cvt_pk_bf16_f32 v212, v184, v185
	v_cvt_pk_bf16_f32 v213, v186, v187
	v_cvt_pk_bf16_f32 v214, v192, v193
	v_cvt_pk_bf16_f32 v215, v194, v195
	global_store_dwordx4 v167, v[212:215], s[8:9]
	s_add_u32 s8, s8, 0x16000
	s_addc_u32 s9, s9, 0
	v_mul_f32_e32 v184, 0xbfb8aa3b, v64
	v_mul_f32_e32 v185, 0xbfb8aa3b, v65
	v_mul_f32_e32 v186, 0xbfb8aa3b, v66
	v_mul_f32_e32 v187, 0xbfb8aa3b, v67
	v_exp_f32_e32 v184, v184
	v_exp_f32_e32 v185, v185
	v_exp_f32_e32 v186, v186
	v_exp_f32_e32 v187, v187
	s_nop 0
	v_add_f32_e32 v184, 1.0, v184
	v_add_f32_e32 v185, 1.0, v185
	v_add_f32_e32 v186, 1.0, v186
	v_add_f32_e32 v187, 1.0, v187
	v_rcp_f32_e32 v184, v184
	v_rcp_f32_e32 v185, v185
	v_rcp_f32_e32 v186, v186
	v_rcp_f32_e32 v187, v187
	s_nop 0
	v_mul_f32_e32 v184, v64, v184
	v_mul_f32_e32 v185, v65, v185
	v_mul_f32_e32 v186, v66, v186
	v_mul_f32_e32 v187, v67, v187
	v_mul_f32_e32 v184, v68, v184
	v_mul_f32_e32 v185, v69, v185
	v_mul_f32_e32 v186, v70, v186
	v_mul_f32_e32 v187, v71, v187
	v_mul_f32_e32 v192, 0xbfb8aa3b, v72
	v_mul_f32_e32 v193, 0xbfb8aa3b, v73
	v_mul_f32_e32 v194, 0xbfb8aa3b, v74
	v_mul_f32_e32 v195, 0xbfb8aa3b, v75
	v_exp_f32_e32 v192, v192
	v_exp_f32_e32 v193, v193
	v_exp_f32_e32 v194, v194
	v_exp_f32_e32 v195, v195
	s_nop 0
	v_add_f32_e32 v192, 1.0, v192
	v_add_f32_e32 v193, 1.0, v193
	v_add_f32_e32 v194, 1.0, v194
	v_add_f32_e32 v195, 1.0, v195
	v_rcp_f32_e32 v192, v192
	v_rcp_f32_e32 v193, v193
	v_rcp_f32_e32 v194, v194
	v_rcp_f32_e32 v195, v195
	s_nop 0
	v_mul_f32_e32 v192, v72, v192
	v_mul_f32_e32 v193, v73, v193
	v_mul_f32_e32 v194, v74, v194
	v_mul_f32_e32 v195, v75, v195
	v_mul_f32_e32 v192, v76, v192
	v_mul_f32_e32 v193, v77, v193
	v_mul_f32_e32 v194, v78, v194
	v_mul_f32_e32 v195, v79, v195
	v_cvt_pk_bf16_f32 v216, v184, v185
	v_cvt_pk_bf16_f32 v217, v186, v187
	v_cvt_pk_bf16_f32 v218, v192, v193
	v_cvt_pk_bf16_f32 v219, v194, v195
	global_store_dwordx4 v167, v[216:219], s[8:9]
	s_add_u32 s8, s44, 0x80
	s_addc_u32 s9, s46, 0
	v_mul_f32_e32 v184, 0xbfb8aa3b, v80
	v_mul_f32_e32 v185, 0xbfb8aa3b, v81
	v_mul_f32_e32 v186, 0xbfb8aa3b, v82
	v_mul_f32_e32 v187, 0xbfb8aa3b, v83
	v_exp_f32_e32 v184, v184
	v_exp_f32_e32 v185, v185
	v_exp_f32_e32 v186, v186
	v_exp_f32_e32 v187, v187
	s_nop 0
	v_add_f32_e32 v184, 1.0, v184
	v_add_f32_e32 v185, 1.0, v185
	v_add_f32_e32 v186, 1.0, v186
	v_add_f32_e32 v187, 1.0, v187
	v_rcp_f32_e32 v184, v184
	v_rcp_f32_e32 v185, v185
	v_rcp_f32_e32 v186, v186
	v_rcp_f32_e32 v187, v187
	s_nop 0
	v_mul_f32_e32 v184, v80, v184
	v_mul_f32_e32 v185, v81, v185
	v_mul_f32_e32 v186, v82, v186
	v_mul_f32_e32 v187, v83, v187
	v_mul_f32_e32 v184, v84, v184
	v_mul_f32_e32 v185, v85, v185
	v_mul_f32_e32 v186, v86, v186
	v_mul_f32_e32 v187, v87, v187
	v_mul_f32_e32 v192, 0xbfb8aa3b, v88
	v_mul_f32_e32 v193, 0xbfb8aa3b, v89
	v_mul_f32_e32 v194, 0xbfb8aa3b, v90
	v_mul_f32_e32 v195, 0xbfb8aa3b, v91
	v_exp_f32_e32 v192, v192
	v_exp_f32_e32 v193, v193
	v_exp_f32_e32 v194, v194
	v_exp_f32_e32 v195, v195
	s_nop 0
	v_add_f32_e32 v192, 1.0, v192
	v_add_f32_e32 v193, 1.0, v193
	v_add_f32_e32 v194, 1.0, v194
	v_add_f32_e32 v195, 1.0, v195
	v_rcp_f32_e32 v192, v192
	v_rcp_f32_e32 v193, v193
	v_rcp_f32_e32 v194, v194
	v_rcp_f32_e32 v195, v195
	s_nop 0
	v_mul_f32_e32 v192, v88, v192
	v_mul_f32_e32 v193, v89, v193
	v_mul_f32_e32 v194, v90, v194
	v_mul_f32_e32 v195, v91, v195
	v_mul_f32_e32 v192, v92, v192
	v_mul_f32_e32 v193, v93, v193
	v_mul_f32_e32 v194, v94, v194
	v_mul_f32_e32 v195, v95, v195
	v_cvt_pk_bf16_f32 v200, v184, v185
	v_cvt_pk_bf16_f32 v201, v186, v187
	v_cvt_pk_bf16_f32 v202, v192, v193
	v_cvt_pk_bf16_f32 v203, v194, v195
	global_store_dwordx4 v167, v[200:203], s[8:9]
	s_add_u32 s8, s8, 0x16000
	s_addc_u32 s9, s9, 0
	v_mul_f32_e32 v184, 0xbfb8aa3b, v96
	v_mul_f32_e32 v185, 0xbfb8aa3b, v97
	v_mul_f32_e32 v186, 0xbfb8aa3b, v98
	v_mul_f32_e32 v187, 0xbfb8aa3b, v99
	v_exp_f32_e32 v184, v184
	v_exp_f32_e32 v185, v185
	v_exp_f32_e32 v186, v186
	v_exp_f32_e32 v187, v187
	s_nop 0
	v_add_f32_e32 v184, 1.0, v184
	v_add_f32_e32 v185, 1.0, v185
	v_add_f32_e32 v186, 1.0, v186
	v_add_f32_e32 v187, 1.0, v187
	v_rcp_f32_e32 v184, v184
	v_rcp_f32_e32 v185, v185
	v_rcp_f32_e32 v186, v186
	v_rcp_f32_e32 v187, v187
	s_nop 0
	v_mul_f32_e32 v184, v96, v184
	v_mul_f32_e32 v185, v97, v185
	v_mul_f32_e32 v186, v98, v186
	v_mul_f32_e32 v187, v99, v187
	v_mul_f32_e32 v184, v100, v184
	v_mul_f32_e32 v185, v101, v185
	v_mul_f32_e32 v186, v102, v186
	v_mul_f32_e32 v187, v103, v187
	v_mul_f32_e32 v192, 0xbfb8aa3b, v104
	v_mul_f32_e32 v193, 0xbfb8aa3b, v105
	v_mul_f32_e32 v194, 0xbfb8aa3b, v106
	v_mul_f32_e32 v195, 0xbfb8aa3b, v107
	v_exp_f32_e32 v192, v192
	v_exp_f32_e32 v193, v193
	v_exp_f32_e32 v194, v194
	v_exp_f32_e32 v195, v195
	s_nop 0
	v_add_f32_e32 v192, 1.0, v192
	v_add_f32_e32 v193, 1.0, v193
	v_add_f32_e32 v194, 1.0, v194
	v_add_f32_e32 v195, 1.0, v195
	v_rcp_f32_e32 v192, v192
	v_rcp_f32_e32 v193, v193
	v_rcp_f32_e32 v194, v194
	v_rcp_f32_e32 v195, v195
	s_nop 0
	v_mul_f32_e32 v192, v104, v192
	v_mul_f32_e32 v193, v105, v193
	v_mul_f32_e32 v194, v106, v194
	v_mul_f32_e32 v195, v107, v195
	v_mul_f32_e32 v192, v108, v192
	v_mul_f32_e32 v193, v109, v193
	v_mul_f32_e32 v194, v110, v194
	v_mul_f32_e32 v195, v111, v195
	v_cvt_pk_bf16_f32 v204, v184, v185
	v_cvt_pk_bf16_f32 v205, v186, v187
	v_cvt_pk_bf16_f32 v206, v192, v193
	v_cvt_pk_bf16_f32 v207, v194, v195
	global_store_dwordx4 v167, v[204:207], s[8:9]
	s_add_u32 s8, s8, 0x16000
	s_addc_u32 s9, s9, 0
	v_mul_f32_e32 v184, 0xbfb8aa3b, v112
	v_mul_f32_e32 v185, 0xbfb8aa3b, v113
	v_mul_f32_e32 v186, 0xbfb8aa3b, v114
	v_mul_f32_e32 v187, 0xbfb8aa3b, v115
	v_exp_f32_e32 v184, v184
	v_exp_f32_e32 v185, v185
	v_exp_f32_e32 v186, v186
	v_exp_f32_e32 v187, v187
	s_nop 0
	v_add_f32_e32 v184, 1.0, v184
	v_add_f32_e32 v185, 1.0, v185
	v_add_f32_e32 v186, 1.0, v186
	v_add_f32_e32 v187, 1.0, v187
	v_rcp_f32_e32 v184, v184
	v_rcp_f32_e32 v185, v185
	v_rcp_f32_e32 v186, v186
	v_rcp_f32_e32 v187, v187
	s_nop 0
	v_mul_f32_e32 v184, v112, v184
	v_mul_f32_e32 v185, v113, v185
	v_mul_f32_e32 v186, v114, v186
	v_mul_f32_e32 v187, v115, v187
	v_mul_f32_e32 v184, v120, v184
	v_mul_f32_e32 v185, v121, v185
	v_mul_f32_e32 v186, v122, v186
	v_mul_f32_e32 v187, v123, v187
	v_mul_f32_e32 v192, 0xbfb8aa3b, v124
	v_mul_f32_e32 v193, 0xbfb8aa3b, v125
	v_mul_f32_e32 v194, 0xbfb8aa3b, v126
	v_mul_f32_e32 v195, 0xbfb8aa3b, v127
	v_exp_f32_e32 v192, v192
	v_exp_f32_e32 v193, v193
	v_exp_f32_e32 v194, v194
	v_exp_f32_e32 v195, v195
	s_nop 0
	v_add_f32_e32 v192, 1.0, v192
	v_add_f32_e32 v193, 1.0, v193
	v_add_f32_e32 v194, 1.0, v194
	v_add_f32_e32 v195, 1.0, v195
	v_rcp_f32_e32 v192, v192
	v_rcp_f32_e32 v193, v193
	v_rcp_f32_e32 v194, v194
	v_rcp_f32_e32 v195, v195
	s_nop 0
	v_mul_f32_e32 v192, v124, v192
	v_mul_f32_e32 v193, v125, v193
	v_mul_f32_e32 v194, v126, v194
	v_mul_f32_e32 v195, v127, v195
	v_mul_f32_e32 v192, v140, v192
	v_mul_f32_e32 v193, v141, v193
	v_mul_f32_e32 v194, v142, v194
	v_mul_f32_e32 v195, v143, v195
	v_cvt_pk_bf16_f32 v208, v184, v185
	v_cvt_pk_bf16_f32 v209, v186, v187
	v_cvt_pk_bf16_f32 v210, v192, v193
	v_cvt_pk_bf16_f32 v211, v194, v195
	global_store_dwordx4 v167, v[208:211], s[8:9]
	s_add_u32 s8, s8, 0x16000
	s_addc_u32 s9, s9, 0
	v_mul_f32_e32 v184, 0xbfb8aa3b, v144
	v_mul_f32_e32 v185, 0xbfb8aa3b, v145
	v_mul_f32_e32 v186, 0xbfb8aa3b, v146
	v_mul_f32_e32 v187, 0xbfb8aa3b, v147
	v_exp_f32_e32 v184, v184
	v_exp_f32_e32 v185, v185
	v_exp_f32_e32 v186, v186
	v_exp_f32_e32 v187, v187
	s_nop 0
	v_add_f32_e32 v184, 1.0, v184
	v_add_f32_e32 v185, 1.0, v185
	v_add_f32_e32 v186, 1.0, v186
	v_add_f32_e32 v187, 1.0, v187
	v_rcp_f32_e32 v184, v184
	v_rcp_f32_e32 v185, v185
	v_rcp_f32_e32 v186, v186
	v_rcp_f32_e32 v187, v187
	s_nop 0
	v_mul_f32_e32 v184, v144, v184
	v_mul_f32_e32 v185, v145, v185
	v_mul_f32_e32 v186, v146, v186
	v_mul_f32_e32 v187, v147, v187
	v_mul_f32_e32 v184, v148, v184
	v_mul_f32_e32 v185, v149, v185
	v_mul_f32_e32 v186, v150, v186
	v_mul_f32_e32 v187, v151, v187
	v_mul_f32_e32 v192, 0xbfb8aa3b, v152
	v_mul_f32_e32 v193, 0xbfb8aa3b, v153
	v_mul_f32_e32 v194, 0xbfb8aa3b, v154
	v_mul_f32_e32 v195, 0xbfb8aa3b, v155
	v_exp_f32_e32 v192, v192
	v_exp_f32_e32 v193, v193
	v_exp_f32_e32 v194, v194
	v_exp_f32_e32 v195, v195
	s_nop 0
	v_add_f32_e32 v192, 1.0, v192
	v_add_f32_e32 v193, 1.0, v193
	v_add_f32_e32 v194, 1.0, v194
	v_add_f32_e32 v195, 1.0, v195
	v_rcp_f32_e32 v192, v192
	v_rcp_f32_e32 v193, v193
	v_rcp_f32_e32 v194, v194
	v_rcp_f32_e32 v195, v195
	s_nop 0
	v_mul_f32_e32 v192, v152, v192
	v_mul_f32_e32 v193, v153, v193
	v_mul_f32_e32 v194, v154, v194
	v_mul_f32_e32 v195, v155, v195
	v_mul_f32_e32 v192, v156, v192
	v_mul_f32_e32 v193, v157, v193
	v_mul_f32_e32 v194, v158, v194
	v_mul_f32_e32 v195, v159, v195
	v_cvt_pk_bf16_f32 v212, v184, v185
	v_cvt_pk_bf16_f32 v213, v186, v187
	v_cvt_pk_bf16_f32 v214, v192, v193
	v_cvt_pk_bf16_f32 v215, v194, v195
	global_store_dwordx4 v167, v[212:215], s[8:9]
	s_add_u32 s8, s8, 0x16000
	s_addc_u32 s9, s9, 0
	v_mul_f32_e32 v184, 0xbfb8aa3b, v168
	v_mul_f32_e32 v185, 0xbfb8aa3b, v169
	v_mul_f32_e32 v186, 0xbfb8aa3b, v170
	v_mul_f32_e32 v187, 0xbfb8aa3b, v171
	v_exp_f32_e32 v184, v184
	v_exp_f32_e32 v185, v185
	v_exp_f32_e32 v186, v186
	v_exp_f32_e32 v187, v187
	s_nop 0
	v_add_f32_e32 v184, 1.0, v184
	v_add_f32_e32 v185, 1.0, v185
	v_add_f32_e32 v186, 1.0, v186
	v_add_f32_e32 v187, 1.0, v187
	v_rcp_f32_e32 v184, v184
	v_rcp_f32_e32 v185, v185
	v_rcp_f32_e32 v186, v186
	v_rcp_f32_e32 v187, v187
	s_nop 0
	v_mul_f32_e32 v184, v168, v184
	v_mul_f32_e32 v185, v169, v185
	v_mul_f32_e32 v186, v170, v186
	v_mul_f32_e32 v187, v171, v187
	v_mul_f32_e32 v184, v172, v184
	v_mul_f32_e32 v185, v173, v185
	v_mul_f32_e32 v186, v174, v186
	v_mul_f32_e32 v187, v175, v187
	v_mul_f32_e32 v192, 0xbfb8aa3b, v176
	v_mul_f32_e32 v193, 0xbfb8aa3b, v177
	v_mul_f32_e32 v194, 0xbfb8aa3b, v178
	v_mul_f32_e32 v195, 0xbfb8aa3b, v179
	v_exp_f32_e32 v192, v192
	v_exp_f32_e32 v193, v193
	v_exp_f32_e32 v194, v194
	v_exp_f32_e32 v195, v195
	s_nop 0
	v_add_f32_e32 v192, 1.0, v192
	v_add_f32_e32 v193, 1.0, v193
	v_add_f32_e32 v194, 1.0, v194
	v_add_f32_e32 v195, 1.0, v195
	v_rcp_f32_e32 v192, v192
	v_rcp_f32_e32 v193, v193
	v_rcp_f32_e32 v194, v194
	v_rcp_f32_e32 v195, v195
	s_nop 0
	v_mul_f32_e32 v192, v176, v192
	v_mul_f32_e32 v193, v177, v193
	v_mul_f32_e32 v194, v178, v194
	v_mul_f32_e32 v195, v179, v195
	v_mul_f32_e32 v192, v180, v192
	v_mul_f32_e32 v193, v181, v193
	v_mul_f32_e32 v194, v182, v194
	v_mul_f32_e32 v195, v183, v195
	v_cvt_pk_bf16_f32 v216, v184, v185
	v_cvt_pk_bf16_f32 v217, v186, v187
	v_cvt_pk_bf16_f32 v218, v192, v193
	v_cvt_pk_bf16_f32 v219, v194, v195
	global_store_dwordx4 v167, v[216:219], s[8:9]
	s_mov_b32 s48, 1
	s_add_u32 s10, s10, s11
	s_cmp_lt_u32 s10, s50
	s_cbranch_scc1 .Lggu0_tile

.LBB0_197:
	s_mul_i32 s2, s34, 12
	v_readlane_b32 s20, v162, 12
	s_or_b32 s35, s2, 3
	v_readlane_b32 s21, v162, 13
	s_cmp_ge_u32 s35, s21
	v_readlane_b32 s22, v162, 14
	v_readlane_b32 s23, v162, 15
	s_cbranch_scc1 .LBB0_247
	s_waitcnt vmcnt(0)
	v_readlane_b32 s4, v163, 17
	v_readlane_b32 s5, v163, 18
	s_barrier
	v_lshrrev_b32_e32 v0, 6, v128
	v_readfirstlane_b32 s20, v0
	s_cmp_lg_u32 s20, 1
	s_cbranch_scc1 .Lxb0_ninv
	buffer_inv sc1
.Lxb0_ninv:
	s_barrier
	s_and_saveexec_b64 s[2:3], s[4:5]
	s_cbranch_execz .LBB0_246
	s_waitcnt vmcnt(0) lgkmcnt(0)
	ds_read_b32 v2, v117 offset:53248
	ds_read_b32 v3, v117 offset:53252
	v_readlane_b32 s4, v163, 62
	v_readlane_b32 s5, v163, 63
	v_readlane_b32 s36, v162, 60
	s_nop 1
	s_add_u32 s36, s36, 1
	s_nop 2
	v_writelane_b32 v162, s36, 60
	global_atomic_add v0, v117, v129, s[4:5] offset:64 sc0
	s_waitcnt lgkmcnt(0)
	v_mul_lo_u32 v2, v2, s36
	v_mul_lo_u32 v3, v3, s36
	v_readlane_b32 s4, v162, 2
	v_readlane_b32 s5, v162, 3
	s_waitcnt vmcnt(0)
	v_add_u32_e32 v0, 1, v0
	s_nop 0
	v_cmp_eq_u32_e32 vcc, v0, v2
	s_nop 3
	s_cbranch_vccz .Lxb0_poll
	buffer_wbl2 sc1
	s_waitcnt vmcnt(0)
	global_atomic_add v117, v129, s[4:5] offset:64

.Lxb0_done:
.LBB0_246:
	s_or_b64 exec, exec, s[2:3]
	s_waitcnt vmcnt(0) lgkmcnt(0)
	s_barrier

.LBB0_267:
	s_mul_i32 s2, s34, 12
	v_readlane_b32 s20, v162, 12
	s_add_i32 s35, s2, 4
	v_readlane_b32 s21, v162, 13
	s_cmp_ge_i32 s35, s21
	v_readlane_b32 s22, v162, 14
	v_readlane_b32 s23, v162, 15
	s_cbranch_scc1 .LBB0_317
	s_waitcnt vmcnt(0)
	v_readlane_b32 s4, v163, 17
	v_readlane_b32 s5, v163, 18
	s_barrier
	v_lshrrev_b32_e32 v0, 6, v128
	v_readfirstlane_b32 s20, v0
	s_cmp_lg_u32 s20, 1
	s_cbranch_scc1 .Lxb1_ninv
	buffer_inv sc1

.LBB0_323:
	s_or_b64 exec, exec, s[2:3]
	s_mul_i32 s2, s34, 12
	v_readlane_b32 s20, v162, 12
	s_add_i32 s35, s2, 5
	v_readlane_b32 s21, v162, 13
	s_cmp_ge_i32 s35, s21
	v_readlane_b32 s22, v162, 14
	v_readlane_b32 s23, v162, 15
	s_cbranch_scc1 .LBB0_373
	s_waitcnt vmcnt(0)
	v_readlane_b32 s4, v163, 17
	v_readlane_b32 s5, v163, 18
	s_barrier
	v_lshrrev_b32_e32 v0, 6, v128
	v_readfirstlane_b32 s20, v0
	s_cmp_lg_u32 s20, 1
	s_cbranch_scc1 .Lxb2_ninv
	buffer_inv sc1

.LBB0_471:
	s_mul_i32 s2, s34, 12
	v_readlane_b32 s20, v162, 12
	s_add_i32 s35, s2, 6
	v_readlane_b32 s21, v162, 13
	s_cmp_ge_i32 s35, s21
	v_readlane_b32 s22, v162, 14
	v_readlane_b32 s23, v162, 15
	s_cbranch_scc1 .LBB0_521
	s_waitcnt vmcnt(0)
	v_readlane_b32 s4, v163, 17
	v_readlane_b32 s5, v163, 18
	s_barrier
	v_lshrrev_b32_e32 v0, 6, v128
	v_readfirstlane_b32 s20, v0
	s_cmp_lg_u32 s20, 1
	s_cbranch_scc1 .Lxb3_ninv
	buffer_inv sc1

.LBB0_547:
	s_or_b64 exec, exec, s[2:3]
	v_readlane_b32 s2, v162, 36
	v_readlane_b32 s20, v162, 12
	s_add_i32 s35, s2, 7
	v_readlane_b32 s21, v162, 13
	s_cmp_ge_i32 s35, s21
	v_readlane_b32 s22, v162, 14
	v_readlane_b32 s23, v162, 15
	s_cbranch_scc1 .LBB0_597
	s_waitcnt vmcnt(0)
	v_readlane_b32 s4, v163, 17
	v_readlane_b32 s5, v163, 18
	s_barrier
	v_lshrrev_b32_e32 v0, 6, v128
	v_readfirstlane_b32 s20, v0
	s_cmp_lg_u32 s20, 1
	s_cbranch_scc1 .Lxb4_ninv
	buffer_inv sc1

.LBB0_749:
	v_readlane_b32 s2, v162, 36
	v_readlane_b32 s20, v162, 12
	s_add_i32 s35, s2, 8
	v_readlane_b32 s21, v162, 13
	s_cmp_ge_i32 s35, s21
	v_readlane_b32 s22, v162, 14
	v_readlane_b32 s23, v162, 15
	s_cbranch_scc1 .LBB0_799
	s_waitcnt vmcnt(0)
	v_readlane_b32 s4, v163, 17
	v_readlane_b32 s5, v163, 18
	s_barrier
	v_lshrrev_b32_e32 v0, 6, v128
	v_readfirstlane_b32 s20, v0
	s_cmp_lg_u32 s20, 1
	s_cbranch_scc1 .Lxb5_ninv
	buffer_inv sc1

.LBB0_807:
	s_or_b64 exec, exec, s[2:3]
	v_readlane_b32 s2, v162, 36
	v_readlane_b32 s20, v162, 12
	s_add_i32 s35, s2, 9
	v_readlane_b32 s21, v162, 13
	s_cmp_ge_i32 s35, s21
	v_readlane_b32 s22, v162, 14
	v_readlane_b32 s23, v162, 15
	s_cbranch_scc1 .LBB0_857
	s_waitcnt vmcnt(0)
	v_readlane_b32 s4, v163, 17
	v_readlane_b32 s5, v163, 18
	s_barrier
	v_lshrrev_b32_e32 v0, 6, v128
	v_readfirstlane_b32 s20, v0
	s_cmp_lg_u32 s20, 1
	s_cbranch_scc1 .Lxb6_ninv
	buffer_inv sc1

.LBB0_877:
	v_readlane_b32 s2, v162, 36
	v_readlane_b32 s20, v162, 12
	s_add_i32 s35, s2, 10
	v_readlane_b32 s21, v162, 13
	s_cmp_ge_i32 s35, s21
	v_readlane_b32 s22, v162, 14
	v_readlane_b32 s23, v162, 15
	s_cbranch_scc1 .LBB0_927
	s_waitcnt vmcnt(0)
	v_readlane_b32 s4, v163, 17
	v_readlane_b32 s5, v163, 18
	s_barrier
	v_lshrrev_b32_e32 v0, 6, v128
	v_readfirstlane_b32 s20, v0
	s_cmp_lg_u32 s20, 1
	s_cbranch_scc1 .Lxb7_ninv
	buffer_inv sc1

.LBB0_933:
	s_or_b64 exec, exec, s[2:3]
	v_readlane_b32 s2, v162, 36
	v_readlane_b32 s20, v162, 12
	s_add_i32 s35, s2, 11
	v_readlane_b32 s21, v162, 13
	s_cmp_ge_i32 s35, s21
	v_readlane_b32 s22, v162, 14
	v_readlane_b32 s23, v162, 15
	s_cbranch_scc1 .LBB0_983
	s_waitcnt vmcnt(0)
	v_readlane_b32 s4, v163, 17
	v_readlane_b32 s5, v163, 18
	s_barrier
	v_lshrrev_b32_e32 v0, 6, v128
	v_readfirstlane_b32 s20, v0
	s_cmp_lg_u32 s20, 1
	s_cbranch_scc1 .Lxb8_ninv
	buffer_inv sc1

.LBB0_985:
	s_andn2_b64 vcc, exec, s[2:3]
	s_cbranch_vccnz .LBB0_1041
	v_readlane_b32 s10, v164, 0
	v_readlane_b32 s11, v162, 14
	v_readlane_b32 s16, v163, 15
	v_readlane_b32 s17, v163, 16
	v_readlane_b32 s18, v163, 5
	v_readlane_b32 s19, v163, 6
	s_mul_i32 s4, s34, 0x1600000
	s_add_u32 s18, s18, s4
	s_addc_u32 s19, s19, 0
	s_add_u32 s18, s18, 0xb00000
	s_addc_u32 s19, s19, 0
	s_movk_i32 s42, 0x800
	v_and_b32_e32 v220, 63, v128
	v_lshrrev_b32_e32 v221, 6, v128
	v_and_b32_e32 v222, 15, v220
	v_lshrrev_b32_e32 v223, 4, v220
	v_readfirstlane_b32 s40, v221
	v_bfe_u32 v224, v222, 1, 3
	s_lshl_b32 s13, s40, 10
	s_and_b32 s36, s40, 1
	s_lshr_b32 s35, s40, 1
	v_xor_b32_e32 v225, v223, v224
	v_lshlrev_b32_e32 v225, 4, v225
	s_mul_i32 s4, s35, 0x50
	v_add_u32_e32 v226, s4, v222
	v_lshl_add_u32 v116, v226, 7, v225
	v_xor_b32_e32 v118, 64, v116
	s_lshl_b32 s4, s36, 6
	v_add_u32_e32 v227, s4, v222
	v_lshl_add_u32 v119, v227, 7, v225
	v_xor_b32_e32 v160, 64, v119
	v_and_b32_e32 v228, 7, v220
	v_lshrrev_b32_e32 v229, 3, v220
	v_xor_b32_e32 v230, v228, v223
	s_lshl_b32 s4, s36, 2
	v_xor_b32_e32 v230, s4, v230
	v_lshlrev_b32_e32 v230, 4, v230
	s_lshl_b32 s4, s40, 3
	v_add_u32_e32 v231, s4, v229
	v_mad_u32_u24 v161, v231, s42, v230
	v_bfe_u32 v232, v231, 2, 2
	v_and_b32_e32 v233, 3, v231
	v_lshrrev_b32_e32 v234, 4, v231
	v_lshl_add_u32 v232, v232, 3, v233
	s_movk_i32 s4, 0xb00
	v_mad_u32_u24 v232, v234, s4, v232
	v_mad_u32_u24 v165, v232, s42, v230
	v_mul_u32_u24_e32 v167, 0x1600, v226
	v_lshl_add_u32 v167, v223, 4, v167
	s_lshl_b32 s4, s36, 6
	v_add_u32_e32 v167, s4, v167
	s_movk_i32 s50, 0x580
	s_sub_u32 s51, s50, 1
	s_cmp_ge_u32 s10, s50
	s_cbranch_scc1 .Lggu1_done
	s_getreg_b32 s4, hwreg(HW_REG_HW_ID, 0, 4)
	s_and_b32 s4, s4, 1
	s_cmp_eq_u32 s4, 0
	s_cbranch_scc1 .Lggu1_noprio
	s_setprio 1

.LBB0_991:
	v_readlane_b32 s2, v162, 36
	v_readlane_b32 s20, v162, 12
	s_add_i32 s35, s2, 12
	v_readlane_b32 s21, v162, 13
	s_cmp_ge_i32 s35, s21
	v_readlane_b32 s22, v162, 14
	v_readlane_b32 s23, v162, 15
	s_cbranch_scc1 .LBB0_1041
	s_waitcnt vmcnt(0)
	v_readlane_b32 s4, v163, 17
	v_readlane_b32 s5, v163, 18
	s_barrier
	v_lshrrev_b32_e32 v0, 6, v128
	v_readfirstlane_b32 s20, v0
	s_cmp_lg_u32 s20, 1
	s_cbranch_scc1 .Lxb9_ninv
	buffer_inv sc1

.LBB0_1061:
	v_readlane_b32 s2, v162, 36
	v_readlane_b32 s20, v162, 12
	s_add_i32 s35, s2, 13
	v_readlane_b32 s21, v162, 13
	s_cmp_ge_i32 s35, s21
	v_readlane_b32 s22, v162, 14
	v_readlane_b32 s23, v162, 15
	s_cbranch_scc1 .LBB0_1111
	s_waitcnt vmcnt(0)
	v_readlane_b32 s4, v163, 17
	v_readlane_b32 s5, v163, 18
	s_barrier
	v_lshrrev_b32_e32 v0, 6, v128
	v_readfirstlane_b32 s20, v0
	s_cmp_lg_u32 s20, 1
	s_cbranch_scc1 .Lxb10_ninv
	buffer_inv sc1
